# GEMM epilogues no longer drain stores per tile; one s_waitcnt vmcnt(0) at the GEMM phase exit before the grid barrier
# baseline (speedup 1.0000x reference)
.Lg_bf_epi:
	s_waitcnt vmcnt(0) lgkmcnt(0)
	v_add_u32_e32 v66, s11, v113
	v_add_u32_e32 v70, s29, v115
	s_lshl_b32 s98, s64, 1
	s_lshl_b32 s99, s64, 5
	v_mul_lo_u32 v72, v70, s98
	v_lshl_add_u32 v72, v66, 1, v72
	v_add_u32_e32 v73, s98, v72
	v_add_u32_e32 v74, s98, v73
	v_add_u32_e32 v75, s98, v74
	v_add_u32_e32 v76, s99, v72
	v_add_u32_e32 v77, s98, v76
	v_add_u32_e32 v78, s98, v77
	v_add_u32_e32 v79, s98, v78
	v_add_u32_e32 v80, s99, v76
	v_add_u32_e32 v81, s98, v80
	v_add_u32_e32 v82, s98, v81
	v_add_u32_e32 v83, s98, v82
	v_add_u32_e32 v84, s99, v80
	v_add_u32_e32 v85, s98, v84
	v_add_u32_e32 v86, s98, v85
	v_add_u32_e32 v87, s98, v86
	v_cvt_pk_bf16_f32 v88, v62, v63
	global_store_short v72, v88, s[48:49]
	global_store_short_d16_hi v73, v88, s[48:49]
	v_cvt_pk_bf16_f32 v89, v64, v65
	global_store_short v74, v89, s[48:49]
	global_store_short_d16_hi v75, v89, s[48:49]
	v_cvt_pk_bf16_f32 v90, v58, v59
	global_store_short v72, v90, s[48:49] offset:32
	global_store_short_d16_hi v73, v90, s[48:49] offset:32
	v_cvt_pk_bf16_f32 v91, v60, v61
	global_store_short v74, v91, s[48:49] offset:32
	global_store_short_d16_hi v75, v91, s[48:49] offset:32
	v_cvt_pk_bf16_f32 v92, v54, v55
	global_store_short v72, v92, s[48:49] offset:64
	global_store_short_d16_hi v73, v92, s[48:49] offset:64
	v_cvt_pk_bf16_f32 v93, v56, v57
	global_store_short v74, v93, s[48:49] offset:64
	global_store_short_d16_hi v75, v93, s[48:49] offset:64
	v_cvt_pk_bf16_f32 v94, v50, v51
	global_store_short v72, v94, s[48:49] offset:96
	global_store_short_d16_hi v73, v94, s[48:49] offset:96
	v_cvt_pk_bf16_f32 v95, v52, v53
	global_store_short v74, v95, s[48:49] offset:96
	global_store_short_d16_hi v75, v95, s[48:49] offset:96
	v_cvt_pk_bf16_f32 v88, v46, v47
	global_store_short v76, v88, s[48:49]
	global_store_short_d16_hi v77, v88, s[48:49]
	v_cvt_pk_bf16_f32 v89, v48, v49
	global_store_short v78, v89, s[48:49]
	global_store_short_d16_hi v79, v89, s[48:49]
	v_cvt_pk_bf16_f32 v90, v42, v43
	global_store_short v76, v90, s[48:49] offset:32
	global_store_short_d16_hi v77, v90, s[48:49] offset:32
	v_cvt_pk_bf16_f32 v91, v44, v45
	global_store_short v78, v91, s[48:49] offset:32
	global_store_short_d16_hi v79, v91, s[48:49] offset:32
	v_cvt_pk_bf16_f32 v92, v38, v39
	global_store_short v76, v92, s[48:49] offset:64
	global_store_short_d16_hi v77, v92, s[48:49] offset:64
	v_cvt_pk_bf16_f32 v93, v40, v41
	global_store_short v78, v93, s[48:49] offset:64
	global_store_short_d16_hi v79, v93, s[48:49] offset:64
	v_cvt_pk_bf16_f32 v94, v34, v35
	global_store_short v76, v94, s[48:49] offset:96
	global_store_short_d16_hi v77, v94, s[48:49] offset:96
	v_cvt_pk_bf16_f32 v95, v36, v37
	global_store_short v78, v95, s[48:49] offset:96
	global_store_short_d16_hi v79, v95, s[48:49] offset:96
	v_cvt_pk_bf16_f32 v88, v30, v31
	global_store_short v80, v88, s[48:49]
	global_store_short_d16_hi v81, v88, s[48:49]
	v_cvt_pk_bf16_f32 v89, v32, v33
	global_store_short v82, v89, s[48:49]
	global_store_short_d16_hi v83, v89, s[48:49]
	v_cvt_pk_bf16_f32 v90, v26, v27
	global_store_short v80, v90, s[48:49] offset:32
	global_store_short_d16_hi v81, v90, s[48:49] offset:32
	v_cvt_pk_bf16_f32 v91, v28, v29
	global_store_short v82, v91, s[48:49] offset:32
	global_store_short_d16_hi v83, v91, s[48:49] offset:32
	v_cvt_pk_bf16_f32 v92, v22, v23
	global_store_short v80, v92, s[48:49] offset:64
	global_store_short_d16_hi v81, v92, s[48:49] offset:64
	v_cvt_pk_bf16_f32 v93, v24, v25
	global_store_short v82, v93, s[48:49] offset:64
	global_store_short_d16_hi v83, v93, s[48:49] offset:64
	v_cvt_pk_bf16_f32 v94, v18, v19
	global_store_short v80, v94, s[48:49] offset:96
	global_store_short_d16_hi v81, v94, s[48:49] offset:96
	v_cvt_pk_bf16_f32 v95, v20, v21
	global_store_short v82, v95, s[48:49] offset:96
	global_store_short_d16_hi v83, v95, s[48:49] offset:96
	v_cvt_pk_bf16_f32 v88, v12, v13
	global_store_short v84, v88, s[48:49]
	global_store_short_d16_hi v85, v88, s[48:49]
	v_cvt_pk_bf16_f32 v89, v14, v15
	global_store_short v86, v89, s[48:49]
	global_store_short_d16_hi v87, v89, s[48:49]
	v_cvt_pk_bf16_f32 v90, v8, v9
	global_store_short v84, v90, s[48:49] offset:32
	global_store_short_d16_hi v85, v90, s[48:49] offset:32
	v_cvt_pk_bf16_f32 v91, v10, v11
	global_store_short v86, v91, s[48:49] offset:32
	global_store_short_d16_hi v87, v91, s[48:49] offset:32
	v_cvt_pk_bf16_f32 v92, v4, v5
	global_store_short v84, v92, s[48:49] offset:64
	global_store_short_d16_hi v85, v92, s[48:49] offset:64
	v_cvt_pk_bf16_f32 v93, v6, v7
	global_store_short v86, v93, s[48:49] offset:64
	global_store_short_d16_hi v87, v93, s[48:49] offset:64
	v_cvt_pk_bf16_f32 v94, v0, v1
	global_store_short v84, v94, s[48:49] offset:96
	global_store_short_d16_hi v85, v94, s[48:49] offset:96
	v_cvt_pk_bf16_f32 v95, v2, v3
	global_store_short v86, v95, s[48:49] offset:96
	global_store_short_d16_hi v87, v95, s[48:49] offset:96
	s_movk_i32 s96, 0x1000
	s_movk_i32 s97, 0x2000
	s_branch .LBB0_1041

.LBB0_1739:
	s_waitcnt vmcnt(0)
	v_readlane_b32 s36, v255, 16
	v_readlane_b32 s84, v255, 9
	v_readlane_b32 s86, v255, 11
	s_mov_b64 s[4:5], -1
	s_mov_b32 s59, s36
	v_readlane_b32 s85, v255, 10
	v_readlane_b32 s87, v255, 12
	v_readlane_b32 s90, v255, 13
	v_readlane_b32 s91, v255, 14
	v_readlane_b32 s92, v255, 15
	s_movk_i32 s93, 0x680
	s_movk_i32 s94, 0x280
	s_movk_i32 s95, 0xc00
	s_mov_b32 s17, 0x800000
	s_and_b64 vcc, exec, s[74:75]
	s_cbranch_vccnz .LBB0_947
